# code prefetch: at each grid barrier wave 2 of blocks 0-63 loads the 24 KB of code that follow (next phase) into L2 while the block waits
# speedup vs baseline: 1.0008x; 1.0008x over previous
.LBB0_276:
	s_cmp_lt_i32 s59, 2
	s_barrier
	s_cbranch_scc1 .LBB0_330
	s_waitcnt vmcnt(0)
	s_barrier
	s_cmp_eq_u32 s33, 128
	s_cbranch_scc0 .Lpf0_skip
	s_cmp_lt_u32 s30, 64
	s_cbranch_scc0 .Lpf0_skip
	s_getpc_b64 s[98:99]
	s_add_u32 s98, s98, 0x600
	s_addc_u32 s99, s99, 0
	v_lshlrev_b32_e32 v241, 4, v198
	global_load_dwordx4 v[242:245], v241, s[98:99]
	global_load_dwordx4 v[242:245], v241, s[98:99] offset:1024
	global_load_dwordx4 v[242:245], v241, s[98:99] offset:2048
	global_load_dwordx4 v[242:245], v241, s[98:99] offset:3072
	s_add_u32 s98, s98, 0x1000
	s_addc_u32 s99, s99, 0
	global_load_dwordx4 v[242:245], v241, s[98:99]
	global_load_dwordx4 v[242:245], v241, s[98:99] offset:1024
	global_load_dwordx4 v[242:245], v241, s[98:99] offset:2048
	global_load_dwordx4 v[242:245], v241, s[98:99] offset:3072
	s_add_u32 s98, s98, 0x1000
	s_addc_u32 s99, s99, 0
	global_load_dwordx4 v[242:245], v241, s[98:99]
	global_load_dwordx4 v[242:245], v241, s[98:99] offset:1024
	global_load_dwordx4 v[242:245], v241, s[98:99] offset:2048
	global_load_dwordx4 v[242:245], v241, s[98:99] offset:3072
	s_add_u32 s98, s98, 0x1000
	s_addc_u32 s99, s99, 0
	global_load_dwordx4 v[242:245], v241, s[98:99]
	global_load_dwordx4 v[242:245], v241, s[98:99] offset:1024
	global_load_dwordx4 v[242:245], v241, s[98:99] offset:2048
	global_load_dwordx4 v[242:245], v241, s[98:99] offset:3072
	s_add_u32 s98, s98, 0x1000
	s_addc_u32 s99, s99, 0
	global_load_dwordx4 v[242:245], v241, s[98:99]
	global_load_dwordx4 v[242:245], v241, s[98:99] offset:1024
	global_load_dwordx4 v[242:245], v241, s[98:99] offset:2048
	global_load_dwordx4 v[242:245], v241, s[98:99] offset:3072
	s_add_u32 s98, s98, 0x1000
	s_addc_u32 s99, s99, 0
	global_load_dwordx4 v[242:245], v241, s[98:99]
	global_load_dwordx4 v[242:245], v241, s[98:99] offset:1024
	global_load_dwordx4 v[242:245], v241, s[98:99] offset:2048
	global_load_dwordx4 v[242:245], v241, s[98:99] offset:3072
	s_add_u32 s98, s98, 0x1000
	s_addc_u32 s99, s99, 0

.LBB0_338:
	s_cmp_lt_i32 s59, 3
	s_barrier
	s_cbranch_scc1 .LBB0_392
	s_waitcnt vmcnt(0)
	s_barrier
	s_cmp_eq_u32 s33, 128
	s_cbranch_scc0 .Lpf1_skip
	s_cmp_lt_u32 s30, 64
	s_cbranch_scc0 .Lpf1_skip
	s_getpc_b64 s[98:99]
	s_add_u32 s98, s98, 0x600
	s_addc_u32 s99, s99, 0
	v_lshlrev_b32_e32 v241, 4, v198
	global_load_dwordx4 v[242:245], v241, s[98:99]
	global_load_dwordx4 v[242:245], v241, s[98:99] offset:1024
	global_load_dwordx4 v[242:245], v241, s[98:99] offset:2048
	global_load_dwordx4 v[242:245], v241, s[98:99] offset:3072
	s_add_u32 s98, s98, 0x1000
	s_addc_u32 s99, s99, 0
	global_load_dwordx4 v[242:245], v241, s[98:99]
	global_load_dwordx4 v[242:245], v241, s[98:99] offset:1024
	global_load_dwordx4 v[242:245], v241, s[98:99] offset:2048
	global_load_dwordx4 v[242:245], v241, s[98:99] offset:3072
	s_add_u32 s98, s98, 0x1000
	s_addc_u32 s99, s99, 0
	global_load_dwordx4 v[242:245], v241, s[98:99]
	global_load_dwordx4 v[242:245], v241, s[98:99] offset:1024
	global_load_dwordx4 v[242:245], v241, s[98:99] offset:2048
	global_load_dwordx4 v[242:245], v241, s[98:99] offset:3072
	s_add_u32 s98, s98, 0x1000
	s_addc_u32 s99, s99, 0
	global_load_dwordx4 v[242:245], v241, s[98:99]
	global_load_dwordx4 v[242:245], v241, s[98:99] offset:1024
	global_load_dwordx4 v[242:245], v241, s[98:99] offset:2048
	global_load_dwordx4 v[242:245], v241, s[98:99] offset:3072
	s_add_u32 s98, s98, 0x1000
	s_addc_u32 s99, s99, 0
	global_load_dwordx4 v[242:245], v241, s[98:99]
	global_load_dwordx4 v[242:245], v241, s[98:99] offset:1024
	global_load_dwordx4 v[242:245], v241, s[98:99] offset:2048
	global_load_dwordx4 v[242:245], v241, s[98:99] offset:3072
	s_add_u32 s98, s98, 0x1000
	s_addc_u32 s99, s99, 0
	global_load_dwordx4 v[242:245], v241, s[98:99]
	global_load_dwordx4 v[242:245], v241, s[98:99] offset:1024
	global_load_dwordx4 v[242:245], v241, s[98:99] offset:2048
	global_load_dwordx4 v[242:245], v241, s[98:99] offset:3072
	s_add_u32 s98, s98, 0x1000
	s_addc_u32 s99, s99, 0

.LBB0_587:
	s_cmp_lt_i32 s59, 4
	s_waitcnt vmcnt(0)
	s_barrier
	s_cbranch_scc1 .LBB0_641
	s_waitcnt vmcnt(0)
	s_barrier
	s_cmp_eq_u32 s33, 128
	s_cbranch_scc0 .Lpf2_skip
	s_cmp_lt_u32 s30, 64
	s_cbranch_scc0 .Lpf2_skip
	s_getpc_b64 s[98:99]
	s_add_u32 s98, s98, 0x600
	s_addc_u32 s99, s99, 0
	v_lshlrev_b32_e32 v241, 4, v198
	global_load_dwordx4 v[242:245], v241, s[98:99]
	global_load_dwordx4 v[242:245], v241, s[98:99] offset:1024
	global_load_dwordx4 v[242:245], v241, s[98:99] offset:2048
	global_load_dwordx4 v[242:245], v241, s[98:99] offset:3072
	s_add_u32 s98, s98, 0x1000
	s_addc_u32 s99, s99, 0
	global_load_dwordx4 v[242:245], v241, s[98:99]
	global_load_dwordx4 v[242:245], v241, s[98:99] offset:1024
	global_load_dwordx4 v[242:245], v241, s[98:99] offset:2048
	global_load_dwordx4 v[242:245], v241, s[98:99] offset:3072
	s_add_u32 s98, s98, 0x1000
	s_addc_u32 s99, s99, 0
	global_load_dwordx4 v[242:245], v241, s[98:99]
	global_load_dwordx4 v[242:245], v241, s[98:99] offset:1024
	global_load_dwordx4 v[242:245], v241, s[98:99] offset:2048
	global_load_dwordx4 v[242:245], v241, s[98:99] offset:3072
	s_add_u32 s98, s98, 0x1000
	s_addc_u32 s99, s99, 0
	global_load_dwordx4 v[242:245], v241, s[98:99]
	global_load_dwordx4 v[242:245], v241, s[98:99] offset:1024
	global_load_dwordx4 v[242:245], v241, s[98:99] offset:2048
	global_load_dwordx4 v[242:245], v241, s[98:99] offset:3072
	s_add_u32 s98, s98, 0x1000
	s_addc_u32 s99, s99, 0
	global_load_dwordx4 v[242:245], v241, s[98:99]
	global_load_dwordx4 v[242:245], v241, s[98:99] offset:1024
	global_load_dwordx4 v[242:245], v241, s[98:99] offset:2048
	global_load_dwordx4 v[242:245], v241, s[98:99] offset:3072
	s_add_u32 s98, s98, 0x1000
	s_addc_u32 s99, s99, 0
	global_load_dwordx4 v[242:245], v241, s[98:99]
	global_load_dwordx4 v[242:245], v241, s[98:99] offset:1024
	global_load_dwordx4 v[242:245], v241, s[98:99] offset:2048
	global_load_dwordx4 v[242:245], v241, s[98:99] offset:3072
	s_add_u32 s98, s98, 0x1000
	s_addc_u32 s99, s99, 0

.LBB0_657:
	s_cmp_lt_i32 s59, 5
	s_barrier
	s_cbranch_scc1 .LBB0_711
	s_waitcnt vmcnt(0)
	s_barrier
	s_cmp_eq_u32 s33, 128
	s_cbranch_scc0 .Lpf3_skip
	s_cmp_lt_u32 s30, 64
	s_cbranch_scc0 .Lpf3_skip
	s_getpc_b64 s[98:99]
	s_add_u32 s98, s98, 0x600
	s_addc_u32 s99, s99, 0
	v_lshlrev_b32_e32 v241, 4, v198
	global_load_dwordx4 v[242:245], v241, s[98:99]
	global_load_dwordx4 v[242:245], v241, s[98:99] offset:1024
	global_load_dwordx4 v[242:245], v241, s[98:99] offset:2048
	global_load_dwordx4 v[242:245], v241, s[98:99] offset:3072
	s_add_u32 s98, s98, 0x1000
	s_addc_u32 s99, s99, 0
	global_load_dwordx4 v[242:245], v241, s[98:99]
	global_load_dwordx4 v[242:245], v241, s[98:99] offset:1024
	global_load_dwordx4 v[242:245], v241, s[98:99] offset:2048
	global_load_dwordx4 v[242:245], v241, s[98:99] offset:3072
	s_add_u32 s98, s98, 0x1000
	s_addc_u32 s99, s99, 0
	global_load_dwordx4 v[242:245], v241, s[98:99]
	global_load_dwordx4 v[242:245], v241, s[98:99] offset:1024
	global_load_dwordx4 v[242:245], v241, s[98:99] offset:2048
	global_load_dwordx4 v[242:245], v241, s[98:99] offset:3072
	s_add_u32 s98, s98, 0x1000
	s_addc_u32 s99, s99, 0
	global_load_dwordx4 v[242:245], v241, s[98:99]
	global_load_dwordx4 v[242:245], v241, s[98:99] offset:1024
	global_load_dwordx4 v[242:245], v241, s[98:99] offset:2048
	global_load_dwordx4 v[242:245], v241, s[98:99] offset:3072
	s_add_u32 s98, s98, 0x1000
	s_addc_u32 s99, s99, 0
	global_load_dwordx4 v[242:245], v241, s[98:99]
	global_load_dwordx4 v[242:245], v241, s[98:99] offset:1024
	global_load_dwordx4 v[242:245], v241, s[98:99] offset:2048
	global_load_dwordx4 v[242:245], v241, s[98:99] offset:3072
	s_add_u32 s98, s98, 0x1000
	s_addc_u32 s99, s99, 0
	global_load_dwordx4 v[242:245], v241, s[98:99]
	global_load_dwordx4 v[242:245], v241, s[98:99] offset:1024
	global_load_dwordx4 v[242:245], v241, s[98:99] offset:2048
	global_load_dwordx4 v[242:245], v241, s[98:99] offset:3072
	s_add_u32 s98, s98, 0x1000
	s_addc_u32 s99, s99, 0

.LBB0_833:
	s_cmp_lt_i32 s59, 6
	s_waitcnt vmcnt(0)
	s_barrier
	s_cbranch_scc1 .LBB0_887
	s_waitcnt vmcnt(0)
	s_barrier
	s_cmp_eq_u32 s33, 128
	s_cbranch_scc0 .Lpf4_skip
	s_cmp_lt_u32 s30, 64
	s_cbranch_scc0 .Lpf4_skip
	s_getpc_b64 s[98:99]
	s_add_u32 s98, s98, 0x600
	s_addc_u32 s99, s99, 0
	v_lshlrev_b32_e32 v241, 4, v198
	global_load_dwordx4 v[242:245], v241, s[98:99]
	global_load_dwordx4 v[242:245], v241, s[98:99] offset:1024
	global_load_dwordx4 v[242:245], v241, s[98:99] offset:2048
	global_load_dwordx4 v[242:245], v241, s[98:99] offset:3072
	s_add_u32 s98, s98, 0x1000
	s_addc_u32 s99, s99, 0
	global_load_dwordx4 v[242:245], v241, s[98:99]
	global_load_dwordx4 v[242:245], v241, s[98:99] offset:1024
	global_load_dwordx4 v[242:245], v241, s[98:99] offset:2048
	global_load_dwordx4 v[242:245], v241, s[98:99] offset:3072
	s_add_u32 s98, s98, 0x1000
	s_addc_u32 s99, s99, 0
	global_load_dwordx4 v[242:245], v241, s[98:99]
	global_load_dwordx4 v[242:245], v241, s[98:99] offset:1024
	global_load_dwordx4 v[242:245], v241, s[98:99] offset:2048
	global_load_dwordx4 v[242:245], v241, s[98:99] offset:3072
	s_add_u32 s98, s98, 0x1000
	s_addc_u32 s99, s99, 0
	global_load_dwordx4 v[242:245], v241, s[98:99]
	global_load_dwordx4 v[242:245], v241, s[98:99] offset:1024
	global_load_dwordx4 v[242:245], v241, s[98:99] offset:2048
	global_load_dwordx4 v[242:245], v241, s[98:99] offset:3072
	s_add_u32 s98, s98, 0x1000
	s_addc_u32 s99, s99, 0
	global_load_dwordx4 v[242:245], v241, s[98:99]
	global_load_dwordx4 v[242:245], v241, s[98:99] offset:1024
	global_load_dwordx4 v[242:245], v241, s[98:99] offset:2048
	global_load_dwordx4 v[242:245], v241, s[98:99] offset:3072
	s_add_u32 s98, s98, 0x1000
	s_addc_u32 s99, s99, 0
	global_load_dwordx4 v[242:245], v241, s[98:99]
	global_load_dwordx4 v[242:245], v241, s[98:99] offset:1024
	global_load_dwordx4 v[242:245], v241, s[98:99] offset:2048
	global_load_dwordx4 v[242:245], v241, s[98:99] offset:3072
	s_add_u32 s98, s98, 0x1000
	s_addc_u32 s99, s99, 0

.LBB0_986:
	s_cmp_lt_i32 s59, 7
	s_barrier
	s_cbranch_scc1 .LBB0_1040
	s_waitcnt vmcnt(0)
	s_barrier
	s_cmp_eq_u32 s33, 128
	s_cbranch_scc0 .Lpf5_skip
	s_cmp_lt_u32 s30, 64
	s_cbranch_scc0 .Lpf5_skip
	s_getpc_b64 s[98:99]
	s_add_u32 s98, s98, 0x600
	s_addc_u32 s99, s99, 0
	v_lshlrev_b32_e32 v241, 4, v198
	global_load_dwordx4 v[242:245], v241, s[98:99]
	global_load_dwordx4 v[242:245], v241, s[98:99] offset:1024
	global_load_dwordx4 v[242:245], v241, s[98:99] offset:2048
	global_load_dwordx4 v[242:245], v241, s[98:99] offset:3072
	s_add_u32 s98, s98, 0x1000
	s_addc_u32 s99, s99, 0
	global_load_dwordx4 v[242:245], v241, s[98:99]
	global_load_dwordx4 v[242:245], v241, s[98:99] offset:1024
	global_load_dwordx4 v[242:245], v241, s[98:99] offset:2048
	global_load_dwordx4 v[242:245], v241, s[98:99] offset:3072
	s_add_u32 s98, s98, 0x1000
	s_addc_u32 s99, s99, 0
	global_load_dwordx4 v[242:245], v241, s[98:99]
	global_load_dwordx4 v[242:245], v241, s[98:99] offset:1024
	global_load_dwordx4 v[242:245], v241, s[98:99] offset:2048
	global_load_dwordx4 v[242:245], v241, s[98:99] offset:3072
	s_add_u32 s98, s98, 0x1000
	s_addc_u32 s99, s99, 0
	global_load_dwordx4 v[242:245], v241, s[98:99]
	global_load_dwordx4 v[242:245], v241, s[98:99] offset:1024
	global_load_dwordx4 v[242:245], v241, s[98:99] offset:2048
	global_load_dwordx4 v[242:245], v241, s[98:99] offset:3072
	s_add_u32 s98, s98, 0x1000
	s_addc_u32 s99, s99, 0
	global_load_dwordx4 v[242:245], v241, s[98:99]
	global_load_dwordx4 v[242:245], v241, s[98:99] offset:1024
	global_load_dwordx4 v[242:245], v241, s[98:99] offset:2048
	global_load_dwordx4 v[242:245], v241, s[98:99] offset:3072
	s_add_u32 s98, s98, 0x1000
	s_addc_u32 s99, s99, 0
	global_load_dwordx4 v[242:245], v241, s[98:99]
	global_load_dwordx4 v[242:245], v241, s[98:99] offset:1024
	global_load_dwordx4 v[242:245], v241, s[98:99] offset:2048
	global_load_dwordx4 v[242:245], v241, s[98:99] offset:3072
	s_add_u32 s98, s98, 0x1000
	s_addc_u32 s99, s99, 0

.LBB0_1106:
	s_cmp_lt_i32 s59, 8
	s_barrier
	s_cbranch_scc1 .LBB0_1160
	s_waitcnt vmcnt(0)
	s_barrier
	s_cmp_eq_u32 s33, 128
	s_cbranch_scc0 .Lpf6_skip
	s_cmp_lt_u32 s30, 64
	s_cbranch_scc0 .Lpf6_skip
	s_getpc_b64 s[98:99]
	s_add_u32 s98, s98, 0x600
	s_addc_u32 s99, s99, 0
	v_lshlrev_b32_e32 v241, 4, v198
	global_load_dwordx4 v[242:245], v241, s[98:99]
	global_load_dwordx4 v[242:245], v241, s[98:99] offset:1024
	global_load_dwordx4 v[242:245], v241, s[98:99] offset:2048
	global_load_dwordx4 v[242:245], v241, s[98:99] offset:3072
	s_add_u32 s98, s98, 0x1000
	s_addc_u32 s99, s99, 0
	global_load_dwordx4 v[242:245], v241, s[98:99]
	global_load_dwordx4 v[242:245], v241, s[98:99] offset:1024
	global_load_dwordx4 v[242:245], v241, s[98:99] offset:2048
	global_load_dwordx4 v[242:245], v241, s[98:99] offset:3072
	s_add_u32 s98, s98, 0x1000
	s_addc_u32 s99, s99, 0
	global_load_dwordx4 v[242:245], v241, s[98:99]
	global_load_dwordx4 v[242:245], v241, s[98:99] offset:1024
	global_load_dwordx4 v[242:245], v241, s[98:99] offset:2048
	global_load_dwordx4 v[242:245], v241, s[98:99] offset:3072
	s_add_u32 s98, s98, 0x1000
	s_addc_u32 s99, s99, 0
	global_load_dwordx4 v[242:245], v241, s[98:99]
	global_load_dwordx4 v[242:245], v241, s[98:99] offset:1024
	global_load_dwordx4 v[242:245], v241, s[98:99] offset:2048
	global_load_dwordx4 v[242:245], v241, s[98:99] offset:3072
	s_add_u32 s98, s98, 0x1000
	s_addc_u32 s99, s99, 0
	global_load_dwordx4 v[242:245], v241, s[98:99]
	global_load_dwordx4 v[242:245], v241, s[98:99] offset:1024
	global_load_dwordx4 v[242:245], v241, s[98:99] offset:2048
	global_load_dwordx4 v[242:245], v241, s[98:99] offset:3072
	s_add_u32 s98, s98, 0x1000
	s_addc_u32 s99, s99, 0
	global_load_dwordx4 v[242:245], v241, s[98:99]
	global_load_dwordx4 v[242:245], v241, s[98:99] offset:1024
	global_load_dwordx4 v[242:245], v241, s[98:99] offset:2048
	global_load_dwordx4 v[242:245], v241, s[98:99] offset:3072
	s_add_u32 s98, s98, 0x1000
	s_addc_u32 s99, s99, 0

.LBB0_1285:
	s_cmp_lt_i32 s59, 10
	s_waitcnt vmcnt(0)
	s_barrier
	s_cbranch_scc1 .LBB0_1339
	s_waitcnt vmcnt(0)
	s_barrier
	s_cmp_eq_u32 s33, 128
	s_cbranch_scc0 .Lpf7_skip
	s_cmp_lt_u32 s30, 64
	s_cbranch_scc0 .Lpf7_skip
	s_getpc_b64 s[98:99]
	s_add_u32 s98, s98, 0x600
	s_addc_u32 s99, s99, 0
	v_lshlrev_b32_e32 v241, 4, v198
	global_load_dwordx4 v[242:245], v241, s[98:99]
	global_load_dwordx4 v[242:245], v241, s[98:99] offset:1024
	global_load_dwordx4 v[242:245], v241, s[98:99] offset:2048
	global_load_dwordx4 v[242:245], v241, s[98:99] offset:3072
	s_add_u32 s98, s98, 0x1000
	s_addc_u32 s99, s99, 0
	global_load_dwordx4 v[242:245], v241, s[98:99]
	global_load_dwordx4 v[242:245], v241, s[98:99] offset:1024
	global_load_dwordx4 v[242:245], v241, s[98:99] offset:2048
	global_load_dwordx4 v[242:245], v241, s[98:99] offset:3072
	s_add_u32 s98, s98, 0x1000
	s_addc_u32 s99, s99, 0
	global_load_dwordx4 v[242:245], v241, s[98:99]
	global_load_dwordx4 v[242:245], v241, s[98:99] offset:1024
	global_load_dwordx4 v[242:245], v241, s[98:99] offset:2048
	global_load_dwordx4 v[242:245], v241, s[98:99] offset:3072
	s_add_u32 s98, s98, 0x1000
	s_addc_u32 s99, s99, 0
	global_load_dwordx4 v[242:245], v241, s[98:99]
	global_load_dwordx4 v[242:245], v241, s[98:99] offset:1024
	global_load_dwordx4 v[242:245], v241, s[98:99] offset:2048
	global_load_dwordx4 v[242:245], v241, s[98:99] offset:3072
	s_add_u32 s98, s98, 0x1000
	s_addc_u32 s99, s99, 0
	global_load_dwordx4 v[242:245], v241, s[98:99]
	global_load_dwordx4 v[242:245], v241, s[98:99] offset:1024
	global_load_dwordx4 v[242:245], v241, s[98:99] offset:2048
	global_load_dwordx4 v[242:245], v241, s[98:99] offset:3072
	s_add_u32 s98, s98, 0x1000
	s_addc_u32 s99, s99, 0
	global_load_dwordx4 v[242:245], v241, s[98:99]
	global_load_dwordx4 v[242:245], v241, s[98:99] offset:1024
	global_load_dwordx4 v[242:245], v241, s[98:99] offset:2048
	global_load_dwordx4 v[242:245], v241, s[98:99] offset:3072
	s_add_u32 s98, s98, 0x1000
	s_addc_u32 s99, s99, 0

.LBB0_1347:
	s_cmp_lt_i32 s59, 11
	s_barrier
	s_cbranch_scc1 .LBB0_1401
	s_waitcnt vmcnt(0)
	s_barrier
	s_cmp_eq_u32 s33, 128
	s_cbranch_scc0 .Lpf8_skip
	s_cmp_lt_u32 s30, 64
	s_cbranch_scc0 .Lpf8_skip
	s_getpc_b64 s[98:99]
	s_add_u32 s98, s98, 0x600
	s_addc_u32 s99, s99, 0
	v_lshlrev_b32_e32 v241, 4, v198
	global_load_dwordx4 v[242:245], v241, s[98:99]
	global_load_dwordx4 v[242:245], v241, s[98:99] offset:1024
	global_load_dwordx4 v[242:245], v241, s[98:99] offset:2048
	global_load_dwordx4 v[242:245], v241, s[98:99] offset:3072
	s_add_u32 s98, s98, 0x1000
	s_addc_u32 s99, s99, 0
	global_load_dwordx4 v[242:245], v241, s[98:99]
	global_load_dwordx4 v[242:245], v241, s[98:99] offset:1024
	global_load_dwordx4 v[242:245], v241, s[98:99] offset:2048
	global_load_dwordx4 v[242:245], v241, s[98:99] offset:3072
	s_add_u32 s98, s98, 0x1000
	s_addc_u32 s99, s99, 0
	global_load_dwordx4 v[242:245], v241, s[98:99]
	global_load_dwordx4 v[242:245], v241, s[98:99] offset:1024
	global_load_dwordx4 v[242:245], v241, s[98:99] offset:2048
	global_load_dwordx4 v[242:245], v241, s[98:99] offset:3072
	s_add_u32 s98, s98, 0x1000
	s_addc_u32 s99, s99, 0
	global_load_dwordx4 v[242:245], v241, s[98:99]
	global_load_dwordx4 v[242:245], v241, s[98:99] offset:1024
	global_load_dwordx4 v[242:245], v241, s[98:99] offset:2048
	global_load_dwordx4 v[242:245], v241, s[98:99] offset:3072
	s_add_u32 s98, s98, 0x1000
	s_addc_u32 s99, s99, 0
	global_load_dwordx4 v[242:245], v241, s[98:99]
	global_load_dwordx4 v[242:245], v241, s[98:99] offset:1024
	global_load_dwordx4 v[242:245], v241, s[98:99] offset:2048
	global_load_dwordx4 v[242:245], v241, s[98:99] offset:3072
	s_add_u32 s98, s98, 0x1000
	s_addc_u32 s99, s99, 0
	global_load_dwordx4 v[242:245], v241, s[98:99]
	global_load_dwordx4 v[242:245], v241, s[98:99] offset:1024
	global_load_dwordx4 v[242:245], v241, s[98:99] offset:2048
	global_load_dwordx4 v[242:245], v241, s[98:99] offset:3072
	s_add_u32 s98, s98, 0x1000
	s_addc_u32 s99, s99, 0

.LBB0_1558:
	s_cmp_lt_i32 s59, 12
	s_waitcnt lgkmcnt(0)
	s_barrier
	s_cbranch_scc1 .LBB0_1612
	s_waitcnt vmcnt(0)
	s_barrier
	s_cmp_eq_u32 s33, 128
	s_cbranch_scc0 .Lpf9_skip
	s_cmp_lt_u32 s30, 64
	s_cbranch_scc0 .Lpf9_skip
	s_getpc_b64 s[98:99]
	s_add_u32 s98, s98, 0x600
	s_addc_u32 s99, s99, 0
	v_lshlrev_b32_e32 v241, 4, v198
	global_load_dwordx4 v[242:245], v241, s[98:99]
	global_load_dwordx4 v[242:245], v241, s[98:99] offset:1024
	global_load_dwordx4 v[242:245], v241, s[98:99] offset:2048
	global_load_dwordx4 v[242:245], v241, s[98:99] offset:3072
	s_add_u32 s98, s98, 0x1000
	s_addc_u32 s99, s99, 0
	global_load_dwordx4 v[242:245], v241, s[98:99]
	global_load_dwordx4 v[242:245], v241, s[98:99] offset:1024
	global_load_dwordx4 v[242:245], v241, s[98:99] offset:2048
	global_load_dwordx4 v[242:245], v241, s[98:99] offset:3072
	s_add_u32 s98, s98, 0x1000
	s_addc_u32 s99, s99, 0
	global_load_dwordx4 v[242:245], v241, s[98:99]
	global_load_dwordx4 v[242:245], v241, s[98:99] offset:1024
	global_load_dwordx4 v[242:245], v241, s[98:99] offset:2048
	global_load_dwordx4 v[242:245], v241, s[98:99] offset:3072
	s_add_u32 s98, s98, 0x1000
	s_addc_u32 s99, s99, 0
	global_load_dwordx4 v[242:245], v241, s[98:99]
	global_load_dwordx4 v[242:245], v241, s[98:99] offset:1024
	global_load_dwordx4 v[242:245], v241, s[98:99] offset:2048
	global_load_dwordx4 v[242:245], v241, s[98:99] offset:3072
	s_add_u32 s98, s98, 0x1000
	s_addc_u32 s99, s99, 0
	global_load_dwordx4 v[242:245], v241, s[98:99]
	global_load_dwordx4 v[242:245], v241, s[98:99] offset:1024
	global_load_dwordx4 v[242:245], v241, s[98:99] offset:2048
	global_load_dwordx4 v[242:245], v241, s[98:99] offset:3072
	s_add_u32 s98, s98, 0x1000
	s_addc_u32 s99, s99, 0
	global_load_dwordx4 v[242:245], v241, s[98:99]
	global_load_dwordx4 v[242:245], v241, s[98:99] offset:1024
	global_load_dwordx4 v[242:245], v241, s[98:99] offset:2048
	global_load_dwordx4 v[242:245], v241, s[98:99] offset:3072
	s_add_u32 s98, s98, 0x1000
	s_addc_u32 s99, s99, 0

.LBB0_2400:
	s_cmp_lt_i32 s59, 14
	s_waitcnt vmcnt(0)
	s_barrier
	s_cbranch_scc1 .LBB0_2454
	s_waitcnt vmcnt(0)
	s_barrier
	s_cmp_eq_u32 s33, 128
	s_cbranch_scc0 .Lpf10_skip
	s_cmp_lt_u32 s30, 64
	s_cbranch_scc0 .Lpf10_skip
	s_getpc_b64 s[98:99]
	s_add_u32 s98, s98, 0x600
	s_addc_u32 s99, s99, 0
	v_lshlrev_b32_e32 v241, 4, v198
	global_load_dwordx4 v[242:245], v241, s[98:99]
	global_load_dwordx4 v[242:245], v241, s[98:99] offset:1024
	global_load_dwordx4 v[242:245], v241, s[98:99] offset:2048
	global_load_dwordx4 v[242:245], v241, s[98:99] offset:3072
	s_add_u32 s98, s98, 0x1000
	s_addc_u32 s99, s99, 0
	global_load_dwordx4 v[242:245], v241, s[98:99]
	global_load_dwordx4 v[242:245], v241, s[98:99] offset:1024
	global_load_dwordx4 v[242:245], v241, s[98:99] offset:2048
	global_load_dwordx4 v[242:245], v241, s[98:99] offset:3072
	s_add_u32 s98, s98, 0x1000
	s_addc_u32 s99, s99, 0
	global_load_dwordx4 v[242:245], v241, s[98:99]
	global_load_dwordx4 v[242:245], v241, s[98:99] offset:1024
	global_load_dwordx4 v[242:245], v241, s[98:99] offset:2048
	global_load_dwordx4 v[242:245], v241, s[98:99] offset:3072
	s_add_u32 s98, s98, 0x1000
	s_addc_u32 s99, s99, 0
	global_load_dwordx4 v[242:245], v241, s[98:99]
	global_load_dwordx4 v[242:245], v241, s[98:99] offset:1024
	global_load_dwordx4 v[242:245], v241, s[98:99] offset:2048
	global_load_dwordx4 v[242:245], v241, s[98:99] offset:3072
	s_add_u32 s98, s98, 0x1000
	s_addc_u32 s99, s99, 0
	global_load_dwordx4 v[242:245], v241, s[98:99]
	global_load_dwordx4 v[242:245], v241, s[98:99] offset:1024
	global_load_dwordx4 v[242:245], v241, s[98:99] offset:2048
	global_load_dwordx4 v[242:245], v241, s[98:99] offset:3072
	s_add_u32 s98, s98, 0x1000
	s_addc_u32 s99, s99, 0
	global_load_dwordx4 v[242:245], v241, s[98:99]
	global_load_dwordx4 v[242:245], v241, s[98:99] offset:1024
	global_load_dwordx4 v[242:245], v241, s[98:99] offset:2048
	global_load_dwordx4 v[242:245], v241, s[98:99] offset:3072
	s_add_u32 s98, s98, 0x1000
	s_addc_u32 s99, s99, 0

.LBB0_2462:
	s_cmp_lt_i32 s59, 15
	s_barrier
	s_cbranch_scc1 .LBB0_2516
	s_waitcnt vmcnt(0)
	s_barrier
	s_cmp_eq_u32 s33, 128
	s_cbranch_scc0 .Lpf11_skip
	s_cmp_lt_u32 s30, 64
	s_cbranch_scc0 .Lpf11_skip
	s_getpc_b64 s[98:99]
	s_add_u32 s98, s98, 0x600
	s_addc_u32 s99, s99, 0
	v_lshlrev_b32_e32 v241, 4, v198
	global_load_dwordx4 v[242:245], v241, s[98:99]
	global_load_dwordx4 v[242:245], v241, s[98:99] offset:1024
	global_load_dwordx4 v[242:245], v241, s[98:99] offset:2048
	global_load_dwordx4 v[242:245], v241, s[98:99] offset:3072
	s_add_u32 s98, s98, 0x1000
	s_addc_u32 s99, s99, 0
	global_load_dwordx4 v[242:245], v241, s[98:99]
	global_load_dwordx4 v[242:245], v241, s[98:99] offset:1024
	global_load_dwordx4 v[242:245], v241, s[98:99] offset:2048
	global_load_dwordx4 v[242:245], v241, s[98:99] offset:3072
	s_add_u32 s98, s98, 0x1000
	s_addc_u32 s99, s99, 0
	global_load_dwordx4 v[242:245], v241, s[98:99]
	global_load_dwordx4 v[242:245], v241, s[98:99] offset:1024
	global_load_dwordx4 v[242:245], v241, s[98:99] offset:2048
	global_load_dwordx4 v[242:245], v241, s[98:99] offset:3072
	s_add_u32 s98, s98, 0x1000
	s_addc_u32 s99, s99, 0
	global_load_dwordx4 v[242:245], v241, s[98:99]
	global_load_dwordx4 v[242:245], v241, s[98:99] offset:1024
	global_load_dwordx4 v[242:245], v241, s[98:99] offset:2048
	global_load_dwordx4 v[242:245], v241, s[98:99] offset:3072
	s_add_u32 s98, s98, 0x1000
	s_addc_u32 s99, s99, 0
	global_load_dwordx4 v[242:245], v241, s[98:99]
	global_load_dwordx4 v[242:245], v241, s[98:99] offset:1024
	global_load_dwordx4 v[242:245], v241, s[98:99] offset:2048
	global_load_dwordx4 v[242:245], v241, s[98:99] offset:3072
	s_add_u32 s98, s98, 0x1000
	s_addc_u32 s99, s99, 0
	global_load_dwordx4 v[242:245], v241, s[98:99]
	global_load_dwordx4 v[242:245], v241, s[98:99] offset:1024
	global_load_dwordx4 v[242:245], v241, s[98:99] offset:2048
	global_load_dwordx4 v[242:245], v241, s[98:99] offset:3072
	s_add_u32 s98, s98, 0x1000
	s_addc_u32 s99, s99, 0

.LBB0_2579:
	s_cmp_lt_i32 s59, 16
	s_waitcnt vmcnt(0)
	s_barrier
	s_cbranch_scc1 .LBB0_2634
	s_waitcnt vmcnt(0)
	s_barrier
	s_cmp_eq_u32 s33, 128
	s_cbranch_scc0 .Lpf12_skip
	s_cmp_lt_u32 s30, 64
	s_cbranch_scc0 .Lpf12_skip
	s_getpc_b64 s[98:99]
	s_add_u32 s98, s98, 0x600
	s_addc_u32 s99, s99, 0
	v_lshlrev_b32_e32 v241, 4, v198
	global_load_dwordx4 v[242:245], v241, s[98:99]
	global_load_dwordx4 v[242:245], v241, s[98:99] offset:1024
	global_load_dwordx4 v[242:245], v241, s[98:99] offset:2048
	global_load_dwordx4 v[242:245], v241, s[98:99] offset:3072
	s_add_u32 s98, s98, 0x1000
	s_addc_u32 s99, s99, 0
	global_load_dwordx4 v[242:245], v241, s[98:99]
	global_load_dwordx4 v[242:245], v241, s[98:99] offset:1024
	global_load_dwordx4 v[242:245], v241, s[98:99] offset:2048
	global_load_dwordx4 v[242:245], v241, s[98:99] offset:3072
	s_add_u32 s98, s98, 0x1000
	s_addc_u32 s99, s99, 0
	global_load_dwordx4 v[242:245], v241, s[98:99]
	global_load_dwordx4 v[242:245], v241, s[98:99] offset:1024
	global_load_dwordx4 v[242:245], v241, s[98:99] offset:2048
	global_load_dwordx4 v[242:245], v241, s[98:99] offset:3072
	s_add_u32 s98, s98, 0x1000
	s_addc_u32 s99, s99, 0
	global_load_dwordx4 v[242:245], v241, s[98:99]
	global_load_dwordx4 v[242:245], v241, s[98:99] offset:1024
	global_load_dwordx4 v[242:245], v241, s[98:99] offset:2048
	global_load_dwordx4 v[242:245], v241, s[98:99] offset:3072
	s_add_u32 s98, s98, 0x1000
	s_addc_u32 s99, s99, 0
	global_load_dwordx4 v[242:245], v241, s[98:99]
	global_load_dwordx4 v[242:245], v241, s[98:99] offset:1024
	global_load_dwordx4 v[242:245], v241, s[98:99] offset:2048
	global_load_dwordx4 v[242:245], v241, s[98:99] offset:3072
	s_add_u32 s98, s98, 0x1000
	s_addc_u32 s99, s99, 0
	global_load_dwordx4 v[242:245], v241, s[98:99]
	global_load_dwordx4 v[242:245], v241, s[98:99] offset:1024
	global_load_dwordx4 v[242:245], v241, s[98:99] offset:2048
	global_load_dwordx4 v[242:245], v241, s[98:99] offset:3072
	s_add_u32 s98, s98, 0x1000
	s_addc_u32 s99, s99, 0

.LBB0_2702:
	s_cmp_lt_i32 s59, 17
	s_barrier
	s_cbranch_scc1 .LBB0_2756
	s_waitcnt vmcnt(0)
	s_barrier
	s_cmp_eq_u32 s33, 128
	s_cbranch_scc0 .Lpf13_skip
	s_cmp_lt_u32 s30, 64
	s_cbranch_scc0 .Lpf13_skip
	s_getpc_b64 s[98:99]
	s_add_u32 s98, s98, 0x600
	s_addc_u32 s99, s99, 0
	v_lshlrev_b32_e32 v241, 4, v198
	global_load_dwordx4 v[242:245], v241, s[98:99]
	global_load_dwordx4 v[242:245], v241, s[98:99] offset:1024
	global_load_dwordx4 v[242:245], v241, s[98:99] offset:2048
	global_load_dwordx4 v[242:245], v241, s[98:99] offset:3072
	s_add_u32 s98, s98, 0x1000
	s_addc_u32 s99, s99, 0
	global_load_dwordx4 v[242:245], v241, s[98:99]
	global_load_dwordx4 v[242:245], v241, s[98:99] offset:1024
	global_load_dwordx4 v[242:245], v241, s[98:99] offset:2048
	global_load_dwordx4 v[242:245], v241, s[98:99] offset:3072
	s_add_u32 s98, s98, 0x1000
	s_addc_u32 s99, s99, 0
	global_load_dwordx4 v[242:245], v241, s[98:99]
	global_load_dwordx4 v[242:245], v241, s[98:99] offset:1024
	global_load_dwordx4 v[242:245], v241, s[98:99] offset:2048
	global_load_dwordx4 v[242:245], v241, s[98:99] offset:3072
	s_add_u32 s98, s98, 0x1000
	s_addc_u32 s99, s99, 0
	global_load_dwordx4 v[242:245], v241, s[98:99]
	global_load_dwordx4 v[242:245], v241, s[98:99] offset:1024
	global_load_dwordx4 v[242:245], v241, s[98:99] offset:2048
	global_load_dwordx4 v[242:245], v241, s[98:99] offset:3072
	s_add_u32 s98, s98, 0x1000
	s_addc_u32 s99, s99, 0
	global_load_dwordx4 v[242:245], v241, s[98:99]
	global_load_dwordx4 v[242:245], v241, s[98:99] offset:1024
	global_load_dwordx4 v[242:245], v241, s[98:99] offset:2048
	global_load_dwordx4 v[242:245], v241, s[98:99] offset:3072
	s_add_u32 s98, s98, 0x1000
	s_addc_u32 s99, s99, 0
	global_load_dwordx4 v[242:245], v241, s[98:99]
	global_load_dwordx4 v[242:245], v241, s[98:99] offset:1024
	global_load_dwordx4 v[242:245], v241, s[98:99] offset:2048
	global_load_dwordx4 v[242:245], v241, s[98:99] offset:3072
	s_add_u32 s98, s98, 0x1000
	s_addc_u32 s99, s99, 0

.LBB0_2844:
	s_cmp_lt_i32 s59, 18
	s_barrier
	s_cbranch_scc1 .LBB0_2898
	s_waitcnt vmcnt(0)
	s_barrier
	s_cmp_eq_u32 s33, 128
	s_cbranch_scc0 .Lpf14_skip
	s_cmp_lt_u32 s30, 64
	s_cbranch_scc0 .Lpf14_skip
	s_getpc_b64 s[98:99]
	s_add_u32 s98, s98, 0x600
	s_addc_u32 s99, s99, 0
	v_lshlrev_b32_e32 v241, 4, v198
	global_load_dwordx4 v[242:245], v241, s[98:99]
	global_load_dwordx4 v[242:245], v241, s[98:99] offset:1024
	global_load_dwordx4 v[242:245], v241, s[98:99] offset:2048
	global_load_dwordx4 v[242:245], v241, s[98:99] offset:3072
	s_add_u32 s98, s98, 0x1000
	s_addc_u32 s99, s99, 0
	global_load_dwordx4 v[242:245], v241, s[98:99]
	global_load_dwordx4 v[242:245], v241, s[98:99] offset:1024
	global_load_dwordx4 v[242:245], v241, s[98:99] offset:2048
	global_load_dwordx4 v[242:245], v241, s[98:99] offset:3072
	s_add_u32 s98, s98, 0x1000
	s_addc_u32 s99, s99, 0
	global_load_dwordx4 v[242:245], v241, s[98:99]
	global_load_dwordx4 v[242:245], v241, s[98:99] offset:1024
	global_load_dwordx4 v[242:245], v241, s[98:99] offset:2048
	global_load_dwordx4 v[242:245], v241, s[98:99] offset:3072
	s_add_u32 s98, s98, 0x1000
	s_addc_u32 s99, s99, 0
	global_load_dwordx4 v[242:245], v241, s[98:99]
	global_load_dwordx4 v[242:245], v241, s[98:99] offset:1024
	global_load_dwordx4 v[242:245], v241, s[98:99] offset:2048
	global_load_dwordx4 v[242:245], v241, s[98:99] offset:3072
	s_add_u32 s98, s98, 0x1000
	s_addc_u32 s99, s99, 0
	global_load_dwordx4 v[242:245], v241, s[98:99]
	global_load_dwordx4 v[242:245], v241, s[98:99] offset:1024
	global_load_dwordx4 v[242:245], v241, s[98:99] offset:2048
	global_load_dwordx4 v[242:245], v241, s[98:99] offset:3072
	s_add_u32 s98, s98, 0x1000
	s_addc_u32 s99, s99, 0
	global_load_dwordx4 v[242:245], v241, s[98:99]
	global_load_dwordx4 v[242:245], v241, s[98:99] offset:1024
	global_load_dwordx4 v[242:245], v241, s[98:99] offset:2048
	global_load_dwordx4 v[242:245], v241, s[98:99] offset:3072
	s_add_u32 s98, s98, 0x1000
	s_addc_u32 s99, s99, 0

.LBB0_3024:
	s_cmp_lt_i32 s59, 20
	s_waitcnt vmcnt(0)
	s_barrier
	s_cbranch_scc1 .LBB0_3078
	s_waitcnt vmcnt(0)
	s_barrier
	s_cmp_eq_u32 s33, 128
	s_cbranch_scc0 .Lpf15_skip
	s_cmp_lt_u32 s30, 64
	s_cbranch_scc0 .Lpf15_skip
	s_getpc_b64 s[98:99]
	s_add_u32 s98, s98, 0x600
	s_addc_u32 s99, s99, 0
	v_lshlrev_b32_e32 v241, 4, v198
	global_load_dwordx4 v[242:245], v241, s[98:99]
	global_load_dwordx4 v[242:245], v241, s[98:99] offset:1024
	global_load_dwordx4 v[242:245], v241, s[98:99] offset:2048
	global_load_dwordx4 v[242:245], v241, s[98:99] offset:3072
	s_add_u32 s98, s98, 0x1000
	s_addc_u32 s99, s99, 0
	global_load_dwordx4 v[242:245], v241, s[98:99]
	global_load_dwordx4 v[242:245], v241, s[98:99] offset:1024
	global_load_dwordx4 v[242:245], v241, s[98:99] offset:2048
	global_load_dwordx4 v[242:245], v241, s[98:99] offset:3072
	s_add_u32 s98, s98, 0x1000
	s_addc_u32 s99, s99, 0
	global_load_dwordx4 v[242:245], v241, s[98:99]
	global_load_dwordx4 v[242:245], v241, s[98:99] offset:1024
	global_load_dwordx4 v[242:245], v241, s[98:99] offset:2048
	global_load_dwordx4 v[242:245], v241, s[98:99] offset:3072
	s_add_u32 s98, s98, 0x1000
	s_addc_u32 s99, s99, 0
	global_load_dwordx4 v[242:245], v241, s[98:99]
	global_load_dwordx4 v[242:245], v241, s[98:99] offset:1024
	global_load_dwordx4 v[242:245], v241, s[98:99] offset:2048
	global_load_dwordx4 v[242:245], v241, s[98:99] offset:3072
	s_add_u32 s98, s98, 0x1000
	s_addc_u32 s99, s99, 0
	global_load_dwordx4 v[242:245], v241, s[98:99]
	global_load_dwordx4 v[242:245], v241, s[98:99] offset:1024
	global_load_dwordx4 v[242:245], v241, s[98:99] offset:2048
	global_load_dwordx4 v[242:245], v241, s[98:99] offset:3072
	s_add_u32 s98, s98, 0x1000
	s_addc_u32 s99, s99, 0
	global_load_dwordx4 v[242:245], v241, s[98:99]
	global_load_dwordx4 v[242:245], v241, s[98:99] offset:1024
	global_load_dwordx4 v[242:245], v241, s[98:99] offset:2048
	global_load_dwordx4 v[242:245], v241, s[98:99] offset:3072
	s_add_u32 s98, s98, 0x1000
	s_addc_u32 s99, s99, 0

.LBB0_3082:
	s_cmp_lt_u32 s59, 21
	s_barrier
	s_cbranch_scc1 .LBB0_3136
	s_waitcnt vmcnt(0)
	s_barrier
	s_cmp_eq_u32 s33, 128
	s_cbranch_scc0 .Lpf16_skip
	s_cmp_lt_u32 s30, 64
	s_cbranch_scc0 .Lpf16_skip
	s_getpc_b64 s[98:99]
	s_add_u32 s98, s98, 0x600
	s_addc_u32 s99, s99, 0
	v_lshlrev_b32_e32 v241, 4, v198
	global_load_dwordx4 v[242:245], v241, s[98:99]
	global_load_dwordx4 v[242:245], v241, s[98:99] offset:1024
	global_load_dwordx4 v[242:245], v241, s[98:99] offset:2048
	global_load_dwordx4 v[242:245], v241, s[98:99] offset:3072
	s_add_u32 s98, s98, 0x1000
	s_addc_u32 s99, s99, 0
	global_load_dwordx4 v[242:245], v241, s[98:99]
	global_load_dwordx4 v[242:245], v241, s[98:99] offset:1024
	global_load_dwordx4 v[242:245], v241, s[98:99] offset:2048
	global_load_dwordx4 v[242:245], v241, s[98:99] offset:3072
	s_add_u32 s98, s98, 0x1000
	s_addc_u32 s99, s99, 0
	global_load_dwordx4 v[242:245], v241, s[98:99]
	global_load_dwordx4 v[242:245], v241, s[98:99] offset:1024
	global_load_dwordx4 v[242:245], v241, s[98:99] offset:2048
	global_load_dwordx4 v[242:245], v241, s[98:99] offset:3072
	s_add_u32 s98, s98, 0x1000
	s_addc_u32 s99, s99, 0
	global_load_dwordx4 v[242:245], v241, s[98:99]
	global_load_dwordx4 v[242:245], v241, s[98:99] offset:1024
	global_load_dwordx4 v[242:245], v241, s[98:99] offset:2048
	global_load_dwordx4 v[242:245], v241, s[98:99] offset:3072
	s_add_u32 s98, s98, 0x1000
	s_addc_u32 s99, s99, 0
	global_load_dwordx4 v[242:245], v241, s[98:99]
	global_load_dwordx4 v[242:245], v241, s[98:99] offset:1024
	global_load_dwordx4 v[242:245], v241, s[98:99] offset:2048
	global_load_dwordx4 v[242:245], v241, s[98:99] offset:3072
	s_add_u32 s98, s98, 0x1000
	s_addc_u32 s99, s99, 0
	global_load_dwordx4 v[242:245], v241, s[98:99]
	global_load_dwordx4 v[242:245], v241, s[98:99] offset:1024
	global_load_dwordx4 v[242:245], v241, s[98:99] offset:2048
	global_load_dwordx4 v[242:245], v241, s[98:99] offset:3072
	s_add_u32 s98, s98, 0x1000
	s_addc_u32 s99, s99, 0

.LBB0_3155:
	s_cmp_lt_i32 s59, 22
	s_waitcnt vmcnt(0)
	s_barrier
	s_cbranch_scc1 .LBB0_3209
	s_waitcnt vmcnt(0)
	s_barrier
	s_cmp_eq_u32 s33, 128
	s_cbranch_scc0 .Lpf17_skip
	s_cmp_lt_u32 s30, 64
	s_cbranch_scc0 .Lpf17_skip
	s_getpc_b64 s[98:99]
	s_add_u32 s98, s98, 0x600
	s_addc_u32 s99, s99, 0
	v_lshlrev_b32_e32 v241, 4, v198
	global_load_dwordx4 v[242:245], v241, s[98:99]
	global_load_dwordx4 v[242:245], v241, s[98:99] offset:1024
	global_load_dwordx4 v[242:245], v241, s[98:99] offset:2048
	global_load_dwordx4 v[242:245], v241, s[98:99] offset:3072
	s_add_u32 s98, s98, 0x1000
	s_addc_u32 s99, s99, 0
	global_load_dwordx4 v[242:245], v241, s[98:99]
	global_load_dwordx4 v[242:245], v241, s[98:99] offset:1024
	global_load_dwordx4 v[242:245], v241, s[98:99] offset:2048
	global_load_dwordx4 v[242:245], v241, s[98:99] offset:3072
	s_add_u32 s98, s98, 0x1000
	s_addc_u32 s99, s99, 0
	global_load_dwordx4 v[242:245], v241, s[98:99]
	global_load_dwordx4 v[242:245], v241, s[98:99] offset:1024
	global_load_dwordx4 v[242:245], v241, s[98:99] offset:2048
	global_load_dwordx4 v[242:245], v241, s[98:99] offset:3072
	s_add_u32 s98, s98, 0x1000
	s_addc_u32 s99, s99, 0
	global_load_dwordx4 v[242:245], v241, s[98:99]
	global_load_dwordx4 v[242:245], v241, s[98:99] offset:1024
	global_load_dwordx4 v[242:245], v241, s[98:99] offset:2048
	global_load_dwordx4 v[242:245], v241, s[98:99] offset:3072
	s_add_u32 s98, s98, 0x1000
	s_addc_u32 s99, s99, 0
	global_load_dwordx4 v[242:245], v241, s[98:99]
	global_load_dwordx4 v[242:245], v241, s[98:99] offset:1024
	global_load_dwordx4 v[242:245], v241, s[98:99] offset:2048
	global_load_dwordx4 v[242:245], v241, s[98:99] offset:3072
	s_add_u32 s98, s98, 0x1000
	s_addc_u32 s99, s99, 0
	global_load_dwordx4 v[242:245], v241, s[98:99]
	global_load_dwordx4 v[242:245], v241, s[98:99] offset:1024
	global_load_dwordx4 v[242:245], v241, s[98:99] offset:2048
	global_load_dwordx4 v[242:245], v241, s[98:99] offset:3072
	s_add_u32 s98, s98, 0x1000
	s_addc_u32 s99, s99, 0

.LBB0_3217:
	s_cmp_lt_i32 s59, 23
	s_barrier
	s_cbranch_scc1 .LBB0_3271
	s_waitcnt vmcnt(0)
	s_barrier
	s_cmp_eq_u32 s33, 128
	s_cbranch_scc0 .Lpf18_skip
	s_cmp_lt_u32 s30, 64
	s_cbranch_scc0 .Lpf18_skip
	s_getpc_b64 s[98:99]
	s_add_u32 s98, s98, 0x600
	s_addc_u32 s99, s99, 0
	v_lshlrev_b32_e32 v241, 4, v198
	global_load_dwordx4 v[242:245], v241, s[98:99]
	global_load_dwordx4 v[242:245], v241, s[98:99] offset:1024
	global_load_dwordx4 v[242:245], v241, s[98:99] offset:2048
	global_load_dwordx4 v[242:245], v241, s[98:99] offset:3072
	s_add_u32 s98, s98, 0x1000
	s_addc_u32 s99, s99, 0
	global_load_dwordx4 v[242:245], v241, s[98:99]
	global_load_dwordx4 v[242:245], v241, s[98:99] offset:1024
	global_load_dwordx4 v[242:245], v241, s[98:99] offset:2048
	global_load_dwordx4 v[242:245], v241, s[98:99] offset:3072
	s_add_u32 s98, s98, 0x1000
	s_addc_u32 s99, s99, 0
	global_load_dwordx4 v[242:245], v241, s[98:99]
	global_load_dwordx4 v[242:245], v241, s[98:99] offset:1024
	global_load_dwordx4 v[242:245], v241, s[98:99] offset:2048
	global_load_dwordx4 v[242:245], v241, s[98:99] offset:3072
	s_add_u32 s98, s98, 0x1000
	s_addc_u32 s99, s99, 0
	global_load_dwordx4 v[242:245], v241, s[98:99]
	global_load_dwordx4 v[242:245], v241, s[98:99] offset:1024
	global_load_dwordx4 v[242:245], v241, s[98:99] offset:2048
	global_load_dwordx4 v[242:245], v241, s[98:99] offset:3072
	s_add_u32 s98, s98, 0x1000
	s_addc_u32 s99, s99, 0
	global_load_dwordx4 v[242:245], v241, s[98:99]
	global_load_dwordx4 v[242:245], v241, s[98:99] offset:1024
	global_load_dwordx4 v[242:245], v241, s[98:99] offset:2048
	global_load_dwordx4 v[242:245], v241, s[98:99] offset:3072
	s_add_u32 s98, s98, 0x1000
	s_addc_u32 s99, s99, 0
	global_load_dwordx4 v[242:245], v241, s[98:99]
	global_load_dwordx4 v[242:245], v241, s[98:99] offset:1024
	global_load_dwordx4 v[242:245], v241, s[98:99] offset:2048
	global_load_dwordx4 v[242:245], v241, s[98:99] offset:3072
	s_add_u32 s98, s98, 0x1000
	s_addc_u32 s99, s99, 0

.LBB0_3341:
	s_cmp_lt_i32 s59, 24
	s_waitcnt lgkmcnt(0)
	s_barrier
	s_cbranch_scc1 .LBB0_3395
	s_waitcnt vmcnt(0)
	s_barrier
	s_cmp_eq_u32 s33, 128
	s_cbranch_scc0 .Lpf19_skip
	s_cmp_lt_u32 s30, 64
	s_cbranch_scc0 .Lpf19_skip
	s_getpc_b64 s[98:99]
	s_add_u32 s98, s98, 0x600
	s_addc_u32 s99, s99, 0
	v_lshlrev_b32_e32 v241, 4, v198
	global_load_dwordx4 v[242:245], v241, s[98:99]
	global_load_dwordx4 v[242:245], v241, s[98:99] offset:1024
	global_load_dwordx4 v[242:245], v241, s[98:99] offset:2048
	global_load_dwordx4 v[242:245], v241, s[98:99] offset:3072
	s_add_u32 s98, s98, 0x1000
	s_addc_u32 s99, s99, 0
	global_load_dwordx4 v[242:245], v241, s[98:99]
	global_load_dwordx4 v[242:245], v241, s[98:99] offset:1024
	global_load_dwordx4 v[242:245], v241, s[98:99] offset:2048
	global_load_dwordx4 v[242:245], v241, s[98:99] offset:3072
	s_add_u32 s98, s98, 0x1000
	s_addc_u32 s99, s99, 0
	global_load_dwordx4 v[242:245], v241, s[98:99]
	global_load_dwordx4 v[242:245], v241, s[98:99] offset:1024
	global_load_dwordx4 v[242:245], v241, s[98:99] offset:2048
	global_load_dwordx4 v[242:245], v241, s[98:99] offset:3072
	s_add_u32 s98, s98, 0x1000
	s_addc_u32 s99, s99, 0
	global_load_dwordx4 v[242:245], v241, s[98:99]
	global_load_dwordx4 v[242:245], v241, s[98:99] offset:1024
	global_load_dwordx4 v[242:245], v241, s[98:99] offset:2048
	global_load_dwordx4 v[242:245], v241, s[98:99] offset:3072
	s_add_u32 s98, s98, 0x1000
	s_addc_u32 s99, s99, 0
	global_load_dwordx4 v[242:245], v241, s[98:99]
	global_load_dwordx4 v[242:245], v241, s[98:99] offset:1024
	global_load_dwordx4 v[242:245], v241, s[98:99] offset:2048
	global_load_dwordx4 v[242:245], v241, s[98:99] offset:3072
	s_add_u32 s98, s98, 0x1000
	s_addc_u32 s99, s99, 0
	global_load_dwordx4 v[242:245], v241, s[98:99]
	global_load_dwordx4 v[242:245], v241, s[98:99] offset:1024
	global_load_dwordx4 v[242:245], v241, s[98:99] offset:2048
	global_load_dwordx4 v[242:245], v241, s[98:99] offset:3072
	s_add_u32 s98, s98, 0x1000
	s_addc_u32 s99, s99, 0
